# A/B: one static s_setprio 1 for the older half (waves 0-3) on the K-loop + fixup variant
# speedup vs baseline: 1.0038x; 1.0038x over previous
; #define LAS __attribute__((address_space(3)))
; template <class T> __device__ __forceinline__ T* lnd(T* p) { asm volatile("" : "+s"(p)); return p; }
; __global__ void __launch_bounds__(512, 2) mega_fwd(Params p) {
;     extern __shared__ __attribute__((aligned(16))) unsigned char lds[];
;     cg::grid_group grid = cg::this_grid();
;     unsigned char* ws = lnd(p.ws);
;     LAS unsigned char* ldsl = (LAS unsigned char*)lds;
;     const int G = gridDim.x, bid = blockIdx.x;
;     volatile LAS unsigned* xst = (volatile LAS unsigned*)(ldsl + LDS_STAGE);
;     if (threadIdx.x < 4) xst[threadIdx.x] = 0u;
;     __syncthreads();
;     const XcdBarrier xbar = xcd_barrier_post((unsigned*)(ws + OFF_BAR), xst);
_Z8mega_fwd6Params:
	s_load_dwordx4 s[68:71], s[0:1], 0x90
	s_load_dword s22, s[0:1], 0xa0
	s_add_u32 s6, s0, 0x98
	v_and_b32_e32 v252, 0x3ff, v0
	s_addc_u32 s7, s1, 0
	s_waitcnt lgkmcnt(0)
	s_mov_b64 s[76:77], s[68:69]
	v_readfirstlane_b32 s26, v252
	s_nop 3
	s_cmp_lt_u32 s26, 0x100
	s_cbranch_scc0 .Lprio_skip
	s_setprio 1
